# grid barrier: non-leader workgroups poll the global generation word instead of the per-XCD one (one hop less on the release path); every workgroup still does its own buffer_inv
# baseline (speedup 1.0000x reference)
; __device__ __forceinline__ unsigned xb_ld(unsigned* p)              { return __hip_atomic_load(p, __ATOMIC_RELAXED, __HIP_MEMORY_SCOPE_AGENT); }
; __device__ __forceinline__ unsigned xb_add(unsigned* p, unsigned v) { return __hip_atomic_fetch_add(p, v, __ATOMIC_RELAXED, __HIP_MEMORY_SCOPE_AGENT); }
; #define XB_SPIN(cond, bar) do { unsigned _sp = 0; while (cond) { __builtin_amdgcn_s_sleep(1); \
;     if ((++_sp & 255u) == 0u) { if (xb_ld(&(bar)[XB_TMO])) break; if (_sp > XB_SPIN_CAP) { atomicAdd(&(bar)[XB_TMO], 1u); break; } } } } while (0)
; __device__ __forceinline__ void xcd_barrier(const XcdBarrier& b, int tid) {
;     ...
;         const unsigned old = xb_add(&bar[XB_XSUB(b.x)], 1u);
;         const unsigned gen = old / nloc;
;         if (old + 1u == (gen + 1u) * nloc) {
;             __builtin_amdgcn_fence(__ATOMIC_RELEASE, "agent");
;             asm volatile("s_waitcnt vmcnt(0)" ::: "memory");
;             const unsigned og = xb_add(&bar[XB_TOP], 1u);
;             const unsigned tg = og / nx;
;             if (og + 1u == (tg + 1u) * nx) xb_add(&bar[XB_TOPGEN], 1u);
;             else XB_SPIN(xb_ld(&bar[XB_TOPGEN]) == tg, bar);
;             __builtin_amdgcn_fence(__ATOMIC_ACQUIRE, "agent");
;             xb_add(&bar[XB_XGEN(b.x)], 1u);
;             asm volatile("s_waitcnt vmcnt(0)" ::: "memory");
;         } else {
;             XB_SPIN(xb_ld(&bar[XB_XGEN(b.x)]) == gen, bar);
.LBB0_838:
	s_or_b64 exec, exec, s[2:3]
	v_cvt_f32_u32_e32 v5, v3
	s_waitcnt vmcnt(0)
	v_readfirstlane_b32 s2, v4
	v_sub_u32_e32 v4, 0, v3
	v_rcp_iflag_f32_e32 v5, v5
	v_add_u32_e32 v6, s2, v0
	v_mul_f32_e32 v5, 0x4f7ffffe, v5
	v_cvt_u32_f32_e32 v5, v5
	v_mul_lo_u32 v0, v4, v5
	v_mul_hi_u32 v0, v5, v0
	v_add_u32_e32 v0, v5, v0
	v_mul_hi_u32 v0, v6, v0
	v_mul_lo_u32 v4, v0, v3
	v_sub_u32_e32 v4, v6, v4
	v_add_u32_e32 v5, 1, v0
	v_cmp_ge_u32_e32 vcc, v4, v3
	s_nop 1
	v_cndmask_b32_e32 v0, v0, v5, vcc
	v_sub_u32_e32 v5, v4, v3
	v_cndmask_b32_e32 v4, v4, v5, vcc
	v_add_u32_e32 v5, 1, v0
	v_cmp_ge_u32_e32 vcc, v4, v3
	v_add_u32_e32 v4, 1, v6
	s_nop 0
	v_cndmask_b32_e32 v0, v0, v5, vcc
	v_mul_lo_u32 v5, v3, v0
	v_add_u32_e32 v3, v5, v3
	v_cmp_ne_u32_e32 vcc, v4, v3
	s_and_saveexec_b64 s[2:3], vcc
	s_xor_b64 s[2:3], exec, s[2:3]
	s_cbranch_execz .LBB0_852
	v_readlane_b32 s4, v253, 22
	v_readlane_b32 s5, v253, 23
	s_waitcnt lgkmcnt(0)
	s_nop 3
	global_load_dword v2, v1, s[4:5] sc1
	s_waitcnt vmcnt(0)
	v_cmp_eq_u32_e32 vcc, v2, v0
	s_and_saveexec_b64 s[4:5], vcc
	s_cbranch_execz .LBB0_851
	s_mov_b32 s8, 1
	s_mov_b64 s[6:7], 0
	s_branch .LBB0_842
